# RMSNorm row loops: 64-lane sum of squares by DPP adds + permlane16/32 swaps instead of six dependent ds_bpermute round trips
# speedup vs baseline: 1.0044x; 1.0044x over previous
; DI void phase_ln(const Params& p, int layer, int sub, bool first, bool final_, const u16* M, int glayer, int goff) {
;     ...
;     if (M) {
; #pragma unroll
;       for (int j = 0; j < 4; ++j) {
;         const int c = j * 256 + lane * 4;
;         v[j].x += pgm[j].x * __uint_as_float(mm[j].x << 16);
;         v[j].y += pgm[j].y * __uint_as_float(mm[j].x & 0xffff0000u);
;         v[j].z += pgm[j].z * __uint_as_float(mm[j].y << 16);
;         v[j].w += pgm[j].w * __uint_as_float(mm[j].y & 0xffff0000u);
;         if (!final_) {
;           const f32x4v t_ = {v[j].x, v[j].y, v[j].z, v[j].w};
;           __builtin_nontemporal_store(t_, (f32x4v*)(p.out + (size_t)row * DM + c));
;         }
;       }
;     }
;     float ss = 0.f;
; #pragma unroll
;     for (int j = 0; j < 4; ++j) ss += v[j].x * v[j].x + v[j].y * v[j].y + v[j].z * v[j].z + v[j].w * v[j].w;
; #pragma unroll
;     for (int o = 1; o < 64; o <<= 1) ss += __shfl_xor(ss, o);
;     const float rstd = rsqrtf(ss * (1.f / 1024.f) + 1e-6f);
;     if (final_) {
; #pragma unroll
;       for (int j = 0; j < 4; ++j) {
;         float4 o4 = {v[j].x * rstd * pg[j].x, v[j].y * rstd * pg[j].y, v[j].z * rstd * pg[j].z, v[j].w * rstd * pg[j].w};
;         const f32x4v t_ = {o4.x, o4.y, o4.z, o4.w};
;         __builtin_nontemporal_store(t_, (f32x4v*)(p.out + (size_t)row * DM + j * 256 + lane * 4));
;       }
.LBB0_41:
	s_or_b64 exec, exec, s[10:11]
	s_waitcnt vmcnt(3)
	v_lshlrev_b32_e32 v118, 16, v102
	v_and_b32_e32 v119, 0xffff0000, v102
	v_lshlrev_b32_e32 v102, 16, v103
	v_and_b32_e32 v103, 0xffff0000, v103
	v_pk_fma_f32 v[28:29], v[44:45], v[102:103], v[28:29]
	s_waitcnt vmcnt(2)
	v_lshlrev_b32_e32 v102, 16, v100
	v_and_b32_e32 v103, 0xffff0000, v100
	v_pk_fma_f32 v[26:27], v[42:43], v[118:119], v[26:27]
	v_pk_fma_f32 v[30:31], v[50:51], v[102:103], v[30:31]
	v_lshlrev_b32_e32 v100, 16, v101
	v_and_b32_e32 v101, 0xffff0000, v101
	v_pk_fma_f32 v[32:33], v[52:53], v[100:101], v[32:33]
	v_mov_b32_e32 v100, v30
	v_mov_b32_e32 v101, v26
	v_pk_mul_f32 v[100:101], v[100:101], v[100:101]
	v_mov_b32_e32 v102, v31
	v_mov_b32_e32 v103, v27
	v_pk_fma_f32 v[100:101], v[102:103], v[102:103], v[100:101]
	v_mov_b32_e32 v102, v32
	v_mov_b32_e32 v103, v28
	v_pk_fma_f32 v[100:101], v[102:103], v[102:103], v[100:101]
	s_waitcnt vmcnt(1)
	v_lshlrev_b32_e32 v102, 16, v96
	v_and_b32_e32 v103, 0xffff0000, v96
	v_pk_fma_f32 v[102:103], v[62:63], v[102:103], v[18:19]
	v_lshlrev_b32_e32 v18, 16, v97
	v_and_b32_e32 v19, 0xffff0000, v97
	v_pk_fma_f32 v[96:97], v[64:65], v[18:19], v[20:21]
	s_waitcnt vmcnt(0)
	v_lshlrev_b32_e32 v18, 16, v94
	v_and_b32_e32 v19, 0xffff0000, v94
	v_pk_fma_f32 v[22:23], v[66:67], v[18:19], v[22:23]
	v_lshlrev_b32_e32 v18, 16, v95
	v_and_b32_e32 v19, 0xffff0000, v95
	v_pk_fma_f32 v[24:25], v[68:69], v[18:19], v[24:25]
	v_mov_b32_e32 v18, v22
	v_mov_b32_e32 v19, v102
	v_pk_mul_f32 v[18:19], v[18:19], v[18:19]
	v_mov_b32_e32 v20, v23
	v_mov_b32_e32 v21, v103
	v_mov_b32_e32 v118, v33
	v_mov_b32_e32 v119, v29
	v_pk_fma_f32 v[18:19], v[20:21], v[20:21], v[18:19]
	v_mov_b32_e32 v20, v24
	v_mov_b32_e32 v21, v96
	v_pk_fma_f32 v[100:101], v[118:119], v[118:119], v[100:101]
	v_mov_b32_e32 v94, v25
	v_mov_b32_e32 v95, v97
	v_pk_fma_f32 v[18:19], v[20:21], v[20:21], v[18:19]
	v_add_f32_e32 v0, v100, v101
	v_pk_fma_f32 v[18:19], v[94:95], v[94:95], v[18:19]
	v_add_u32_e32 v82, 1, v82
	v_add_f32_e32 v0, v19, v0
	v_add_f32_e32 v0, v18, v0
	s_nop 1
	v_add_f32_dpp v0, v0, v0 quad_perm:[1,0,3,2] row_mask:0xf bank_mask:0xf
	v_mov_b32_e32 v100, v88
	v_mov_b32_e32 v101, v89
	v_mov_b32_e32 v94, v92
	v_mov_b32_e32 v95, v93
	s_nop 1
	v_add_f32_dpp v0, v0, v0 quad_perm:[2,3,0,1] row_mask:0xf bank_mask:0xf
	v_mov_b32_e32 v88, v112
	v_mov_b32_e32 v89, v113
	v_mov_b32_e32 v92, v116
	v_mov_b32_e32 v93, v117
	s_nop 1
	v_add_f32_dpp v0, v0, v0 row_half_mirror row_mask:0xf bank_mask:0xf
	s_nop 1
	v_add_f32_dpp v0, v0, v0 row_mirror row_mask:0xf bank_mask:0xf
	v_mov_b32_e32 v18, v0
	s_nop 1
	v_permlane16_swap_b32_e32 v0, v18
	v_add_f32_e32 v0, v0, v18
	v_mov_b32_e32 v18, v0
	s_nop 1
	v_permlane32_swap_b32_e32 v0, v18
	v_add_f32_e32 v0, v0, v18
	v_fmamk_f32 v0, v0, 0x3a800000, v205
	v_mul_f32_e32 v18, 0x4b800000, v0
	v_cmp_gt_f32_e32 vcc, s49, v0
	s_nop 1
	v_cndmask_b32_e32 v0, v0, v18, vcc
	v_rsq_f32_e32 v0, v0
	s_nop 0
	v_mul_f32_e32 v18, 0x45800000, v0
	v_cndmask_b32_e32 v0, v0, v18, vcc
	v_pk_mul_f32 v[18:19], v[26:27], v[0:1] op_sel_hi:[1,0]
	v_pk_mul_f32 v[20:21], v[28:29], v[0:1] op_sel_hi:[1,0]
	v_pk_mul_f32 v[18:19], v[34:35], v[18:19]
	v_pk_mul_f32 v[20:21], v[36:37], v[20:21]
	global_store_dwordx4 v[110:111], v[18:21], off offset:-3072 nt
	v_cmp_ge_i32_e32 vcc, v82, v120
	s_or_b64 s[8:9], vcc, s[8:9]
	v_pk_mul_f32 v[18:19], v[30:31], v[0:1] op_sel_hi:[1,0]
	v_pk_mul_f32 v[20:21], v[32:33], v[0:1] op_sel_hi:[1,0]
	v_pk_mul_f32 v[18:19], v[38:39], v[18:19]
	v_pk_mul_f32 v[20:21], v[40:41], v[20:21]
	global_store_dwordx4 v[110:111], v[18:21], off offset:-2048 nt
	v_mov_b32_e32 v26, v2
	v_mov_b32_e32 v27, v3
	v_pk_mul_f32 v[18:19], v[102:103], v[0:1] op_sel_hi:[1,0]
	v_pk_mul_f32 v[20:21], v[96:97], v[0:1] op_sel_hi:[1,0]
	v_pk_mul_f32 v[18:19], v[46:47], v[18:19]
	v_pk_mul_f32 v[20:21], v[48:49], v[20:21]
	global_store_dwordx4 v[110:111], v[18:21], off offset:-1024 nt
	v_mov_b32_e32 v102, v86
	v_mov_b32_e32 v103, v87
	v_pk_mul_f32 v[18:19], v[22:23], v[0:1] op_sel_hi:[1,0]
	v_pk_mul_f32 v[20:21], v[24:25], v[0:1] op_sel_hi:[1,0]
	v_pk_mul_f32 v[18:19], v[58:59], v[18:19]
	v_pk_mul_f32 v[20:21], v[60:61], v[20:21]
	global_store_dwordx4 v[110:111], v[18:21], off nt
	v_lshl_add_u64 v[110:111], v[110:111], 0, s[44:45]
	v_mov_b32_e32 v96, v90
	v_mov_b32_e32 v97, v91
	v_mov_b32_e32 v86, v84
	v_mov_b32_e32 v87, v85
	v_mov_b32_e32 v90, v114
	v_mov_b32_e32 v91, v115
	v_mov_b32_e32 v2, v54
	v_mov_b32_e32 v3, v55
	v_mov_b32_e32 v28, v4
	v_mov_b32_e32 v29, v5
	v_mov_b32_e32 v4, v56
	v_mov_b32_e32 v5, v57
	v_mov_b32_e32 v30, v6
	v_mov_b32_e32 v31, v7
	v_mov_b32_e32 v6, v70
	v_mov_b32_e32 v7, v71
	v_mov_b32_e32 v32, v8
	v_mov_b32_e32 v33, v9
	v_mov_b32_e32 v8, v72
	v_mov_b32_e32 v9, v73
	v_mov_b32_e32 v18, v10
	v_mov_b32_e32 v19, v11
	v_mov_b32_e32 v10, v74
	v_mov_b32_e32 v11, v75
	v_mov_b32_e32 v20, v12
	v_mov_b32_e32 v21, v13
	v_mov_b32_e32 v12, v76
	v_mov_b32_e32 v13, v77
	v_mov_b32_e32 v22, v14
	v_mov_b32_e32 v23, v15
	v_mov_b32_e32 v14, v78
	v_mov_b32_e32 v15, v79
	v_mov_b32_e32 v24, v16
	v_mov_b32_e32 v25, v17
	v_mov_b32_e32 v16, v80
	v_mov_b32_e32 v17, v81
	s_andn2_b64 exec, exec, s[8:9]
	s_cbranch_execz .LBB0_47

; DI void phase_ln(const Params& p, int layer, int sub, bool first, bool final_, const u16* M, int glayer, int goff) {
;     ...
;     if (M) {
; #pragma unroll
;       for (int j = 0; j < 4; ++j) {
;         const int c = j * 256 + lane * 4;
;         v[j].x += pgm[j].x * __uint_as_float(mm[j].x << 16);
;         v[j].y += pgm[j].y * __uint_as_float(mm[j].x & 0xffff0000u);
;         v[j].z += pgm[j].z * __uint_as_float(mm[j].y << 16);
;         v[j].w += pgm[j].w * __uint_as_float(mm[j].y & 0xffff0000u);
;         if (!final_) {
;           const f32x4v t_ = {v[j].x, v[j].y, v[j].z, v[j].w};
;           __builtin_nontemporal_store(t_, (f32x4v*)(p.out + (size_t)row * DM + c));
;         }
;       }
;     }
;     float ss = 0.f;
; #pragma unroll
;     for (int j = 0; j < 4; ++j) ss += v[j].x * v[j].x + v[j].y * v[j].y + v[j].z * v[j].z + v[j].w * v[j].w;
; #pragma unroll
;     for (int o = 1; o < 64; o <<= 1) ss += __shfl_xor(ss, o);
;     const float rstd = rsqrtf(ss * (1.f / 1024.f) + 1e-6f);
;     if (final_) {
; #pragma unroll
;       for (int j = 0; j < 4; ++j) {
;         float4 o4 = {v[j].x * rstd * pg[j].x, v[j].y * rstd * pg[j].y, v[j].z * rstd * pg[j].z, v[j].w * rstd * pg[j].w};
;         const f32x4v t_ = {o4.x, o4.y, o4.z, o4.w};
;         __builtin_nontemporal_store(t_, (f32x4v*)(p.out + (size_t)row * DM + j * 256 + lane * 4));
;       }
;     } else {
; #pragma unroll
;       for (int j = 0; j < 4; ++j) {
;         const int c = j * 256 + lane * 4;
;         const float a0 = v[j].x * rstd * pg[j].x + psh[j].x;
;         const float a1 = v[j].y * rstd * pg[j].y + psh[j].y;
;         const float a2 = v[j].z * rstd * pg[j].z + psh[j].z;
;         const float a3 = v[j].w * rstd * pg[j].w + psh[j].w;
;         u32x2 o2 = {pk_bf16(a0, a1), pk_bf16(a2, a3)};
;         *(u32x2*)(H + (size_t)row * DM + c) = o2;
;       }
;     }
.LBB0_85:
	s_or_b64 exec, exec, s[10:11]
	s_waitcnt vmcnt(3)
	v_lshlrev_b32_e32 v148, 16, v108
	v_and_b32_e32 v149, 0xffff0000, v108
	v_lshlrev_b32_e32 v108, 16, v109
	v_and_b32_e32 v109, 0xffff0000, v109
	v_pk_fma_f32 v[32:33], v[44:45], v[108:109], v[32:33]
	s_waitcnt vmcnt(2)
	v_lshlrev_b32_e32 v108, 16, v106
	v_and_b32_e32 v109, 0xffff0000, v106
	v_lshlrev_b32_e32 v106, 16, v107
	v_and_b32_e32 v107, 0xffff0000, v107
	v_pk_fma_f32 v[28:29], v[60:61], v[106:107], v[28:29]
	s_waitcnt vmcnt(1)
	v_lshlrev_b32_e32 v106, 16, v104
	v_and_b32_e32 v107, 0xffff0000, v104
	v_lshlrev_b32_e32 v104, 16, v105
	v_and_b32_e32 v105, 0xffff0000, v105
	v_pk_fma_f32 v[30:31], v[42:43], v[148:149], v[30:31]
	v_pk_fma_f32 v[26:27], v[58:59], v[108:109], v[26:27]
	v_pk_fma_f32 v[24:25], v[76:77], v[104:105], v[24:25]
	s_waitcnt vmcnt(0)
	v_lshlrev_b32_e32 v104, 16, v98
	v_and_b32_e32 v105, 0xffff0000, v98
	v_lshlrev_b32_e32 v98, 16, v99
	v_and_b32_e32 v99, 0xffff0000, v99
	v_pk_fma_f32 v[20:21], v[80:81], v[98:99], v[20:21]
	v_mov_b32_e32 v98, v26
	v_mov_b32_e32 v99, v30
	v_pk_fma_f32 v[18:19], v[78:79], v[104:105], v[18:19]
	v_pk_mul_f32 v[98:99], v[98:99], v[98:99]
	v_mov_b32_e32 v104, v27
	v_mov_b32_e32 v105, v31
	v_pk_fma_f32 v[98:99], v[104:105], v[104:105], v[98:99]
	v_mov_b32_e32 v104, v28
	v_mov_b32_e32 v105, v32
	v_pk_fma_f32 v[22:23], v[74:75], v[106:107], v[22:23]
	v_pk_fma_f32 v[98:99], v[104:105], v[104:105], v[98:99]
	v_mov_b32_e32 v104, v29
	v_mov_b32_e32 v105, v33
	v_pk_fma_f32 v[98:99], v[104:105], v[104:105], v[98:99]
	v_mov_b32_e32 v104, v18
	v_mov_b32_e32 v105, v22
	v_pk_mul_f32 v[104:105], v[104:105], v[104:105]
	v_mov_b32_e32 v106, v19
	v_mov_b32_e32 v107, v23
	v_pk_fma_f32 v[104:105], v[106:107], v[106:107], v[104:105]
	v_mov_b32_e32 v106, v20
	v_mov_b32_e32 v107, v24
	v_pk_fma_f32 v[104:105], v[106:107], v[106:107], v[104:105]
	v_mov_b32_e32 v106, v21
	v_mov_b32_e32 v107, v25
	v_pk_fma_f32 v[104:105], v[106:107], v[106:107], v[104:105]
	v_add_f32_e32 v98, v98, v99
	v_add_f32_e32 v98, v105, v98
	v_add_f32_e32 v98, v104, v98
	s_nop 1
	v_add_f32_dpp v98, v98, v98 quad_perm:[1,0,3,2] row_mask:0xf bank_mask:0xf
	global_store_dwordx4 v[118:119], v[30:33], off offset:-3072 nt
	global_store_dwordx4 v[118:119], v[26:29], off offset:-2048 nt
	global_store_dwordx4 v[118:119], v[22:25], off offset:-1024 nt
	global_store_dwordx4 v[118:119], v[18:21], off nt
	v_add_u32_e32 v82, 1, v82
	v_lshl_add_u64 v[118:119], v[118:119], 0, s[44:45]
	s_nop 1
	v_add_f32_dpp v98, v98, v98 quad_perm:[2,3,0,1] row_mask:0xf bank_mask:0xf
	v_mov_b32_e32 v108, v86
	v_mov_b32_e32 v109, v87
	v_mov_b32_e32 v106, v88
	v_mov_b32_e32 v107, v89
	s_nop 1
	v_add_f32_dpp v98, v98, v98 row_half_mirror row_mask:0xf bank_mask:0xf
	v_mov_b32_e32 v104, v90
	v_mov_b32_e32 v105, v91
	v_mov_b32_e32 v86, v84
	v_mov_b32_e32 v87, v85
	s_nop 1
	v_add_f32_dpp v98, v98, v98 row_mirror row_mask:0xf bank_mask:0xf
	v_mov_b32_e32 v88, v130
	v_mov_b32_e32 v89, v131
	v_mov_b32_e32 v90, v132
	v_mov_b32_e32 v91, v133
	v_mov_b32_e32 v99, v98
	s_nop 1
	v_permlane16_swap_b32_e32 v98, v99
	v_add_f32_e32 v98, v98, v99
	v_mov_b32_e32 v99, v98
	s_nop 1
	v_permlane32_swap_b32_e32 v98, v99
	v_add_f32_e32 v98, v98, v99
	v_fmamk_f32 v98, v98, 0x3a800000, v205
	v_mul_f32_e32 v99, 0x4b800000, v98
	v_cmp_gt_f32_e32 vcc, s49, v98
	s_nop 1
	v_cndmask_b32_e32 v98, v98, v99, vcc
	v_rsq_f32_e32 v98, v98
	s_nop 0
	v_mul_f32_e32 v99, 0x45800000, v98
	v_cndmask_b32_e32 v98, v98, v99, vcc
	v_pk_mul_f32 v[30:31], v[30:31], v[98:99] op_sel_hi:[1,0]
	v_pk_mul_f32 v[32:33], v[32:33], v[98:99] op_sel_hi:[1,0]
	v_pk_mul_f32 v[26:27], v[26:27], v[98:99] op_sel_hi:[1,0]
	v_pk_mul_f32 v[28:29], v[28:29], v[98:99] op_sel_hi:[1,0]
	v_pk_mul_f32 v[22:23], v[22:23], v[98:99] op_sel_hi:[1,0]
	v_pk_mul_f32 v[24:25], v[24:25], v[98:99] op_sel_hi:[1,0]
	v_pk_mul_f32 v[18:19], v[18:19], v[98:99] op_sel_hi:[1,0]
	v_pk_mul_f32 v[20:21], v[20:21], v[98:99] op_sel_hi:[1,0]
	v_pk_fma_f32 v[30:31], v[126:127], v[30:31], v[34:35]
	v_pk_fma_f32 v[32:33], v[128:129], v[32:33], v[36:37]
	v_pk_fma_f32 v[26:27], v[136:137], v[26:27], v[38:39]
	v_pk_fma_f32 v[28:29], v[138:139], v[28:29], v[40:41]
	v_pk_fma_f32 v[22:23], v[140:141], v[22:23], v[50:51]
	v_pk_fma_f32 v[24:25], v[142:143], v[24:25], v[52:53]
	v_pk_fma_f32 v[18:19], v[144:145], v[18:19], v[70:71]
	v_pk_fma_f32 v[20:21], v[146:147], v[20:21], v[72:73]
	v_cvt_pk_bf16_f32 v30, v30, v31
	v_cvt_pk_bf16_f32 v31, v32, v33
	v_cvt_pk_bf16_f32 v26, v26, v27
	v_cvt_pk_bf16_f32 v27, v28, v29
	v_cvt_pk_bf16_f32 v22, v22, v23
	v_cvt_pk_bf16_f32 v23, v24, v25
	v_cvt_pk_bf16_f32 v18, v18, v19
	v_cvt_pk_bf16_f32 v19, v20, v21
	v_cmp_ge_i32_e32 vcc, v82, v150
	global_store_dwordx2 v[116:117], v[30:31], off
	global_store_dwordx2 v[116:117], v[26:27], off offset:512
	global_store_dwordx2 v[116:117], v[22:23], off offset:1024
	global_store_dwordx2 v[116:117], v[18:19], off offset:1536
	v_lshl_add_u64 v[116:117], v[116:117], 0, s[26:27]
	s_or_b64 s[8:9], vcc, s[8:9]
	v_mov_b32_e32 v98, v92
	v_mov_b32_e32 v99, v93
	v_mov_b32_e32 v92, v134
	v_mov_b32_e32 v93, v135
	v_mov_b32_e32 v30, v2
	v_mov_b32_e32 v31, v3
	v_mov_b32_e32 v2, v46
	v_mov_b32_e32 v3, v47
	v_mov_b32_e32 v32, v4
	v_mov_b32_e32 v33, v5
	v_mov_b32_e32 v4, v48
	v_mov_b32_e32 v5, v49
	v_mov_b32_e32 v26, v6
	v_mov_b32_e32 v27, v7
	v_mov_b32_e32 v6, v54
	v_mov_b32_e32 v7, v55
	v_mov_b32_e32 v28, v8
	v_mov_b32_e32 v29, v9
	v_mov_b32_e32 v8, v56
	v_mov_b32_e32 v9, v57
	v_mov_b32_e32 v22, v10
	v_mov_b32_e32 v23, v11
	v_mov_b32_e32 v10, v62
	v_mov_b32_e32 v11, v63
	v_mov_b32_e32 v24, v12
	v_mov_b32_e32 v25, v13
	v_mov_b32_e32 v12, v64
	v_mov_b32_e32 v13, v65
	v_mov_b32_e32 v18, v14
	v_mov_b32_e32 v19, v15
	v_mov_b32_e32 v14, v66
	v_mov_b32_e32 v15, v67
	v_mov_b32_e32 v20, v16
	v_mov_b32_e32 v21, v17
	v_mov_b32_e32 v16, v68
	v_mov_b32_e32 v17, v69
	s_andn2_b64 exec, exec, s[8:9]
	s_cbranch_execz .LBB0_90

; DI void phase_ln(const Params& p, int layer, int sub, bool first, bool final_, const u16* M, int glayer, int goff) {
;     ...
;     if (M) {
; #pragma unroll
;       for (int j = 0; j < 4; ++j) {
;         const int c = j * 256 + lane * 4;
;         v[j].x += pgm[j].x * __uint_as_float(mm[j].x << 16);
;         v[j].y += pgm[j].y * __uint_as_float(mm[j].x & 0xffff0000u);
;         v[j].z += pgm[j].z * __uint_as_float(mm[j].y << 16);
;         v[j].w += pgm[j].w * __uint_as_float(mm[j].y & 0xffff0000u);
;         if (!final_) {
;           const f32x4v t_ = {v[j].x, v[j].y, v[j].z, v[j].w};
;           __builtin_nontemporal_store(t_, (f32x4v*)(p.out + (size_t)row * DM + c));
;         }
;       }
;     }
;     float ss = 0.f;
; #pragma unroll
;     for (int j = 0; j < 4; ++j) ss += v[j].x * v[j].x + v[j].y * v[j].y + v[j].z * v[j].z + v[j].w * v[j].w;
; #pragma unroll
;     for (int o = 1; o < 64; o <<= 1) ss += __shfl_xor(ss, o);
;     const float rstd = rsqrtf(ss * (1.f / 1024.f) + 1e-6f);
;     if (final_) {
; #pragma unroll
;       for (int j = 0; j < 4; ++j) {
;         float4 o4 = {v[j].x * rstd * pg[j].x, v[j].y * rstd * pg[j].y, v[j].z * rstd * pg[j].z, v[j].w * rstd * pg[j].w};
;         const f32x4v t_ = {o4.x, o4.y, o4.z, o4.w};
;         __builtin_nontemporal_store(t_, (f32x4v*)(p.out + (size_t)row * DM + j * 256 + lane * 4));
;       }
;     } else {
; #pragma unroll
;       for (int j = 0; j < 4; ++j) {
;         const int c = j * 256 + lane * 4;
;         const float a0 = v[j].x * rstd * pg[j].x + psh[j].x;
;         const float a1 = v[j].y * rstd * pg[j].y + psh[j].y;
;         const float a2 = v[j].z * rstd * pg[j].z + psh[j].z;
;         const float a3 = v[j].w * rstd * pg[j].w + psh[j].w;
;         u32x2 o2 = {pk_bf16(a0, a1), pk_bf16(a2, a3)};
;         *(u32x2*)(H + (size_t)row * DM + c) = o2;
;       }
;     }
.LBB0_220:
	s_or_b64 exec, exec, s[10:11]
	s_waitcnt vmcnt(3)
	v_lshlrev_b32_e32 v146, 16, v108
	v_and_b32_e32 v147, 0xffff0000, v108
	v_lshlrev_b32_e32 v108, 16, v109
	v_and_b32_e32 v109, 0xffff0000, v109
	v_pk_fma_f32 v[32:33], v[44:45], v[108:109], v[32:33]
	s_waitcnt vmcnt(2)
	v_lshlrev_b32_e32 v108, 16, v106
	v_and_b32_e32 v109, 0xffff0000, v106
	v_lshlrev_b32_e32 v106, 16, v107
	v_and_b32_e32 v107, 0xffff0000, v107
	v_pk_fma_f32 v[28:29], v[56:57], v[106:107], v[28:29]
	s_waitcnt vmcnt(1)
	v_lshlrev_b32_e32 v106, 16, v100
	v_and_b32_e32 v107, 0xffff0000, v100
	v_lshlrev_b32_e32 v100, 16, v101
	v_and_b32_e32 v101, 0xffff0000, v101
	v_pk_fma_f32 v[30:31], v[42:43], v[146:147], v[30:31]
	v_pk_fma_f32 v[26:27], v[54:55], v[108:109], v[26:27]
	v_pk_fma_f32 v[24:25], v[76:77], v[100:101], v[24:25]
	s_waitcnt vmcnt(0)
	v_lshlrev_b32_e32 v100, 16, v94
	v_and_b32_e32 v101, 0xffff0000, v94
	v_lshlrev_b32_e32 v94, 16, v95
	v_and_b32_e32 v95, 0xffff0000, v95
	v_pk_fma_f32 v[20:21], v[80:81], v[94:95], v[20:21]
	v_mov_b32_e32 v94, v26
	v_mov_b32_e32 v95, v30
	v_pk_fma_f32 v[18:19], v[78:79], v[100:101], v[18:19]
	v_pk_mul_f32 v[94:95], v[94:95], v[94:95]
	v_mov_b32_e32 v100, v27
	v_mov_b32_e32 v101, v31
	v_pk_fma_f32 v[94:95], v[100:101], v[100:101], v[94:95]
	v_mov_b32_e32 v100, v28
	v_mov_b32_e32 v101, v32
	v_pk_fma_f32 v[22:23], v[74:75], v[106:107], v[22:23]
	v_pk_fma_f32 v[94:95], v[100:101], v[100:101], v[94:95]
	v_mov_b32_e32 v100, v29
	v_mov_b32_e32 v101, v33
	v_pk_fma_f32 v[94:95], v[100:101], v[100:101], v[94:95]
	v_mov_b32_e32 v100, v18
	v_mov_b32_e32 v101, v22
	v_pk_mul_f32 v[100:101], v[100:101], v[100:101]
	v_mov_b32_e32 v106, v19
	v_mov_b32_e32 v107, v23
	v_pk_fma_f32 v[100:101], v[106:107], v[106:107], v[100:101]
	v_mov_b32_e32 v106, v20
	v_mov_b32_e32 v107, v24
	v_pk_fma_f32 v[100:101], v[106:107], v[106:107], v[100:101]
	v_mov_b32_e32 v106, v21
	v_mov_b32_e32 v107, v25
	v_pk_fma_f32 v[100:101], v[106:107], v[106:107], v[100:101]
	v_add_f32_e32 v83, v94, v95
	v_add_f32_e32 v83, v101, v83
	v_add_f32_e32 v83, v100, v83
	s_nop 1
	v_add_f32_dpp v83, v83, v83 quad_perm:[1,0,3,2] row_mask:0xf bank_mask:0xf
	global_store_dwordx4 v[116:117], v[30:33], off offset:-3072 nt
	global_store_dwordx4 v[116:117], v[26:29], off offset:-2048 nt
	global_store_dwordx4 v[116:117], v[22:25], off offset:-1024 nt
	global_store_dwordx4 v[116:117], v[18:21], off nt
	v_add_u32_e32 v82, 1, v82
	v_lshl_add_u64 v[116:117], v[116:117], 0, s[44:45]
	s_nop 1
	v_add_f32_dpp v83, v83, v83 quad_perm:[2,3,0,1] row_mask:0xf bank_mask:0xf
	v_mov_b32_e32 v108, v86
	v_mov_b32_e32 v109, v87
	v_mov_b32_e32 v106, v88
	v_mov_b32_e32 v107, v89
	s_nop 1
	v_add_f32_dpp v83, v83, v83 row_half_mirror row_mask:0xf bank_mask:0xf
	v_mov_b32_e32 v100, v90
	v_mov_b32_e32 v101, v91
	v_mov_b32_e32 v86, v84
	v_mov_b32_e32 v87, v85
	s_nop 1
	v_add_f32_dpp v83, v83, v83 row_mirror row_mask:0xf bank_mask:0xf
	v_mov_b32_e32 v88, v132
	v_mov_b32_e32 v89, v133
	v_mov_b32_e32 v90, v134
	v_mov_b32_e32 v91, v135
	v_mov_b32_e32 v94, v83
	s_nop 1
	v_permlane16_swap_b32_e32 v83, v94
	v_add_f32_e32 v83, v83, v94
	v_mov_b32_e32 v94, v83
	s_nop 1
	v_permlane32_swap_b32_e32 v83, v94
	v_add_f32_e32 v83, v83, v94
	v_fmamk_f32 v83, v83, 0x3a800000, v205
	v_mul_f32_e32 v94, 0x4b800000, v83
	v_cmp_gt_f32_e32 vcc, s49, v83
	s_nop 1
	v_cndmask_b32_e32 v83, v83, v94, vcc
	v_rsq_f32_e32 v83, v83
	s_nop 0
	v_mul_f32_e32 v94, 0x45800000, v83
	v_cndmask_b32_e32 v94, v83, v94, vcc
	v_pk_mul_f32 v[30:31], v[30:31], v[94:95] op_sel_hi:[1,0]
	v_pk_mul_f32 v[32:33], v[32:33], v[94:95] op_sel_hi:[1,0]
	v_pk_mul_f32 v[26:27], v[26:27], v[94:95] op_sel_hi:[1,0]
	v_pk_mul_f32 v[28:29], v[28:29], v[94:95] op_sel_hi:[1,0]
	v_pk_mul_f32 v[22:23], v[22:23], v[94:95] op_sel_hi:[1,0]
	v_pk_mul_f32 v[24:25], v[24:25], v[94:95] op_sel_hi:[1,0]
	v_pk_mul_f32 v[18:19], v[18:19], v[94:95] op_sel_hi:[1,0]
	v_pk_mul_f32 v[20:21], v[20:21], v[94:95] op_sel_hi:[1,0]
	v_pk_fma_f32 v[30:31], v[124:125], v[30:31], v[34:35]
	v_pk_fma_f32 v[32:33], v[126:127], v[32:33], v[36:37]
	v_pk_fma_f32 v[26:27], v[128:129], v[26:27], v[38:39]
	v_pk_fma_f32 v[28:29], v[130:131], v[28:29], v[40:41]
	v_pk_fma_f32 v[22:23], v[138:139], v[22:23], v[46:47]
	v_pk_fma_f32 v[24:25], v[140:141], v[24:25], v[48:49]
	v_pk_fma_f32 v[18:19], v[142:143], v[18:19], v[66:67]
	v_pk_fma_f32 v[20:21], v[144:145], v[20:21], v[68:69]
	v_cvt_pk_bf16_f32 v30, v30, v31
	v_cvt_pk_bf16_f32 v31, v32, v33
	v_cvt_pk_bf16_f32 v26, v26, v27
	v_cvt_pk_bf16_f32 v27, v28, v29
	v_cvt_pk_bf16_f32 v22, v22, v23
	v_cvt_pk_bf16_f32 v23, v24, v25
	v_cvt_pk_bf16_f32 v18, v18, v19
	v_cvt_pk_bf16_f32 v19, v20, v21
	v_cmp_ge_i32_e32 vcc, v82, v148
	global_store_dwordx2 v[114:115], v[30:31], off
	global_store_dwordx2 v[114:115], v[26:27], off offset:512
	global_store_dwordx2 v[114:115], v[22:23], off offset:1024
	global_store_dwordx2 v[114:115], v[18:19], off offset:1536
	v_lshl_add_u64 v[114:115], v[114:115], 0, s[14:15]
	s_or_b64 s[8:9], vcc, s[8:9]
	v_mov_b32_e32 v94, v92
	v_mov_b32_e32 v95, v93
	v_mov_b32_e32 v92, v136
	v_mov_b32_e32 v93, v137
	v_mov_b32_e32 v30, v2
	v_mov_b32_e32 v31, v3
	v_mov_b32_e32 v2, v50
	v_mov_b32_e32 v3, v51
	v_mov_b32_e32 v32, v4
	v_mov_b32_e32 v33, v5
	v_mov_b32_e32 v4, v52
	v_mov_b32_e32 v5, v53
	v_mov_b32_e32 v26, v6
	v_mov_b32_e32 v27, v7
	v_mov_b32_e32 v6, v58
	v_mov_b32_e32 v7, v59
	v_mov_b32_e32 v28, v8
	v_mov_b32_e32 v29, v9
	v_mov_b32_e32 v8, v60
	v_mov_b32_e32 v9, v61
	v_mov_b32_e32 v22, v10
	v_mov_b32_e32 v23, v11
	v_mov_b32_e32 v10, v62
	v_mov_b32_e32 v11, v63
	v_mov_b32_e32 v24, v12
	v_mov_b32_e32 v25, v13
	v_mov_b32_e32 v12, v64
	v_mov_b32_e32 v13, v65
	v_mov_b32_e32 v18, v14
	v_mov_b32_e32 v19, v15
	v_mov_b32_e32 v14, v70
	v_mov_b32_e32 v15, v71
	v_mov_b32_e32 v20, v16
	v_mov_b32_e32 v21, v17
	v_mov_b32_e32 v16, v72
	v_mov_b32_e32 v17, v73
	s_andn2_b64 exec, exec, s[8:9]
	s_cbranch_execz .LBB0_237

; DI void phase_ln(const Params& p, int layer, int sub, bool first, bool final_, const u16* M, int glayer, int goff) {
;     ...
;     float ss = 0.f;
; #pragma unroll
;     for (int j = 0; j < 4; ++j) ss += v[j].x * v[j].x + v[j].y * v[j].y + v[j].z * v[j].z + v[j].w * v[j].w;
; #pragma unroll
;     for (int o = 1; o < 64; o <<= 1) ss += __shfl_xor(ss, o);
;     const float rstd = rsqrtf(ss * (1.f / 1024.f) + 1e-6f);
;     if (final_) {
; #pragma unroll
;       for (int j = 0; j < 4; ++j) {
;         float4 o4 = {v[j].x * rstd * pg[j].x, v[j].y * rstd * pg[j].y, v[j].z * rstd * pg[j].z, v[j].w * rstd * pg[j].w};
;         const f32x4v t_ = {o4.x, o4.y, o4.z, o4.w};
;         __builtin_nontemporal_store(t_, (f32x4v*)(p.out + (size_t)row * DM + j * 256 + lane * 4));
;       }
;     } else {
; #pragma unroll
;       for (int j = 0; j < 4; ++j) {
;         const int c = j * 256 + lane * 4;
;         const float a0 = v[j].x * rstd * pg[j].x + psh[j].x;
;         const float a1 = v[j].y * rstd * pg[j].y + psh[j].y;
;         const float a2 = v[j].z * rstd * pg[j].z + psh[j].z;
;         const float a3 = v[j].w * rstd * pg[j].w + psh[j].w;
;         u32x2 o2 = {pk_bf16(a0, a1), pk_bf16(a2, a3)};
;         *(u32x2*)(H + (size_t)row * DM + c) = o2;
;       }
;     }
.LBB0_395:
	s_or_b64 exec, exec, s[10:11]
	s_waitcnt vmcnt(2)
	v_mov_b32_e32 v102, v34
	v_mov_b32_e32 v103, v26
	v_pk_mul_f32 v[102:103], v[102:103], v[102:103]
	v_mov_b32_e32 v104, v35
	v_mov_b32_e32 v105, v27
	v_pk_fma_f32 v[102:103], v[104:105], v[104:105], v[102:103]
	v_mov_b32_e32 v104, v36
	v_mov_b32_e32 v105, v28
	v_pk_fma_f32 v[102:103], v[104:105], v[104:105], v[102:103]
	v_mov_b32_e32 v104, v37
	v_mov_b32_e32 v105, v29
	v_pk_fma_f32 v[102:103], v[104:105], v[104:105], v[102:103]
	s_waitcnt vmcnt(0)
	v_mov_b32_e32 v104, v30
	v_mov_b32_e32 v105, v22
	v_pk_mul_f32 v[104:105], v[104:105], v[104:105]
	v_mov_b32_e32 v106, v31
	v_mov_b32_e32 v107, v23
	v_pk_fma_f32 v[104:105], v[106:107], v[106:107], v[104:105]
	v_mov_b32_e32 v106, v32
	v_mov_b32_e32 v107, v24
	v_pk_fma_f32 v[104:105], v[106:107], v[106:107], v[104:105]
	v_mov_b32_e32 v106, v33
	v_mov_b32_e32 v107, v25
	v_pk_fma_f32 v[104:105], v[106:107], v[106:107], v[104:105]
	v_add_f32_e32 v67, v102, v103
	v_add_f32_e32 v67, v105, v67
	v_add_f32_e32 v67, v104, v67
	s_nop 1
	v_add_f32_dpp v67, v67, v67 quad_perm:[1,0,3,2] row_mask:0xf bank_mask:0xf
	v_add_u32_e32 v66, 1, v66
	s_nop 1
	v_add_f32_dpp v67, v67, v67 quad_perm:[2,3,0,1] row_mask:0xf bank_mask:0xf
	s_nop 1
	v_add_f32_dpp v67, v67, v67 row_half_mirror row_mask:0xf bank_mask:0xf
	s_nop 1
	v_add_f32_dpp v67, v67, v67 row_mirror row_mask:0xf bank_mask:0xf
	v_mov_b32_e32 v75, v67
	s_nop 1
	v_permlane16_swap_b32_e32 v67, v75
	v_add_f32_e32 v67, v67, v75
	v_mov_b32_e32 v75, v67
	s_nop 1
	v_permlane32_swap_b32_e32 v67, v75
	v_add_f32_e32 v67, v67, v75
	v_fmamk_f32 v67, v67, 0x3a800000, v205
	v_mul_f32_e32 v75, 0x4b800000, v67
	v_cmp_gt_f32_e32 vcc, s49, v67
	s_nop 1
	v_cndmask_b32_e32 v67, v67, v75, vcc
	v_rsq_f32_e32 v67, v67
	s_nop 0
	v_mul_f32_e32 v75, 0x45800000, v67
	v_cndmask_b32_e32 v102, v67, v75, vcc
	v_pk_mul_f32 v[22:23], v[22:23], v[102:103] op_sel_hi:[1,0]
	v_pk_mul_f32 v[24:25], v[24:25], v[102:103] op_sel_hi:[1,0]
	v_pk_fma_f32 v[22:23], v[86:87], v[22:23], v[50:51]
	v_pk_fma_f32 v[24:25], v[88:89], v[24:25], v[52:53]
	v_pk_mul_f32 v[26:27], v[26:27], v[102:103] op_sel_hi:[1,0]
	v_pk_mul_f32 v[28:29], v[28:29], v[102:103] op_sel_hi:[1,0]
	v_cvt_pk_bf16_f32 v22, v22, v23
	v_cvt_pk_bf16_f32 v23, v24, v25
	v_pk_mul_f32 v[34:35], v[34:35], v[102:103] op_sel_hi:[1,0]
	v_pk_mul_f32 v[36:37], v[36:37], v[102:103] op_sel_hi:[1,0]
	v_pk_fma_f32 v[26:27], v[78:79], v[26:27], v[38:39]
	v_pk_fma_f32 v[28:29], v[80:81], v[28:29], v[40:41]
	global_store_dwordx2 v[70:71], v[22:23], off offset:1024
	v_pk_mul_f32 v[22:23], v[30:31], v[102:103] op_sel_hi:[1,0]
	v_pk_mul_f32 v[24:25], v[32:33], v[102:103] op_sel_hi:[1,0]
	v_pk_fma_f32 v[34:35], v[82:83], v[34:35], v[42:43]
	v_pk_fma_f32 v[36:37], v[84:85], v[36:37], v[44:45]
	v_cvt_pk_bf16_f32 v26, v26, v27
	v_cvt_pk_bf16_f32 v27, v28, v29
	v_pk_fma_f32 v[22:23], v[90:91], v[22:23], v[62:63]
	v_pk_fma_f32 v[24:25], v[92:93], v[24:25], v[64:65]
	global_store_dwordx2 v[70:71], v[26:27], off
	v_cvt_pk_bf16_f32 v26, v34, v35
	v_cvt_pk_bf16_f32 v27, v36, v37
	v_cvt_pk_bf16_f32 v22, v22, v23
	v_cvt_pk_bf16_f32 v23, v24, v25
	v_cmp_ge_i32_e32 vcc, v66, v94
	global_store_dwordx2 v[70:71], v[26:27], off offset:512
	global_store_dwordx2 v[70:71], v[22:23], off offset:1536
	v_lshl_add_u64 v[70:71], v[70:71], 0, s[54:55]
	s_or_b64 s[8:9], vcc, s[8:9]
	v_mov_b32_e32 v28, v4
	v_mov_b32_e32 v29, v5
	v_mov_b32_e32 v4, v8
	v_mov_b32_e32 v5, v9
	v_mov_b32_e32 v26, v2
	v_mov_b32_e32 v27, v3
	v_mov_b32_e32 v2, v6
	v_mov_b32_e32 v3, v7
	v_mov_b32_e32 v36, v12
	v_mov_b32_e32 v37, v13
	v_mov_b32_e32 v12, v48
	v_mov_b32_e32 v13, v49
	v_mov_b32_e32 v34, v10
	v_mov_b32_e32 v35, v11
	v_mov_b32_e32 v10, v46
	v_mov_b32_e32 v11, v47
	v_mov_b32_e32 v24, v16
	v_mov_b32_e32 v25, v17
	v_mov_b32_e32 v16, v56
	v_mov_b32_e32 v17, v57
	v_mov_b32_e32 v22, v14
	v_mov_b32_e32 v23, v15
	v_mov_b32_e32 v14, v54
	v_mov_b32_e32 v15, v55
	v_mov_b32_e32 v32, v20
	v_mov_b32_e32 v33, v21
	v_mov_b32_e32 v20, v60
	v_mov_b32_e32 v21, v61
	v_mov_b32_e32 v30, v18
	v_mov_b32_e32 v31, v19
	v_mov_b32_e32 v18, v58
	v_mov_b32_e32 v19, v59
	s_andn2_b64 exec, exec, s[8:9]
	s_cbranch_execz .LBB0_400
